# v37: v34 + in-proj K-loop LDS-DMA addressed as SGPR base + 32-bit VGPR offset (16 v_lshl_add_u64, 3 v_mov, 3 v_add_u32 per iteration removed)
# speedup vs baseline: 1.0053x; 1.0053x over previous
; #define G_STAGE(bufoff, gbase, voff) do { _Pragma("unroll") for (int _i = 0; _i < 2; ++_i) \
;     __builtin_amdgcn_global_load_lds((const unsigned*)((const char*)(gbase) + (voff)[_i]), (LAS unsigned*)(lds + (bufoff) + ldsw + _i * 8192), 16, 0, 0); } while (0)
; #define G_LDA(dst, b, h) do { _Pragma("unroll") for (int m = 0; m < 4; ++m) _Pragma("unroll") for (int k = 0; k < 2; ++k) dst[m][k] = *(const LAS bf16x8*)(lds + G_SA(b, h) + aoff + m * 2048 + k * 1024); } while (0)
; #define G_LDB(dst, b, h) do { _Pragma("unroll") for (int n = 0; n < 2; ++n) _Pragma("unroll") for (int k = 0; k < 2; ++k) dst[n][k] = *(const LAS bf16x8*)(lds + G_SB(b, h) + boff + n * 2048 + k * 1024); } while (0)
; #define G_MMA(ai, bj, At, Bt) do { __builtin_amdgcn_s_setprio(1); _Pragma("unroll") for (int m = 0; m < 4; ++m) _Pragma("unroll") for (int n = 0; n < 2; ++n) _Pragma("unroll") for (int k = 0; k < 2; ++k) \
;     acc[ai][bj][m][n] = __builtin_amdgcn_mfma_f32_16x16x32_bf16(Bt[n][k], At[m][k], acc[ai][bj][m][n], 0, 0, 0); __builtin_amdgcn_s_setprio(0); } while (0)
; #define G_WAIT_V(n) asm volatile("s_waitcnt vmcnt(" #n ")" ::: "memory")
; #define G_WAIT_L(n) asm volatile("s_waitcnt lgkmcnt(" #n ")" ::: "memory")
; #define G_BAR __builtin_amdgcn_s_barrier()
; #define G_SCHED __builtin_amdgcn_sched_barrier(0)
; template <int GP> DI void gemm_phase(const Params& p, int l, int which, char* smem, int wv) {
;     ...
;     for (int t = 0; t < cnk; t += 2) {
;       const bool last = (t == cnk - 2);
;       const char* a1 = cA + (size_t)(t + 1) * kstep;
;       const char* a2 = last ? nA : cA + (size_t)(t + 2) * kstep; const char* b2 = last ? nB : cB + (size_t)(t + 2) * kstep;
;       const char* a3 = a2 + kstep; const char* b3 = b2 + kstep;
;       if (last) {
; #pragma unroll
;         for (int i = 0; i < 2; ++i) { vb0[i] = voffB(i, 0, n32); vb1[i] = voffB(i, 1, n32); }
;       }
;       G_LDB(B0, 0, 0); G_SCHED; G_LDA(At, 0, 0); G_STAGE(G_SA(1, 1), a1 + hstep, voffA);
;       G_WAIT_L(8); G_BAR; G_WAIT_L(0); G_MMA(0, 0, At, B0); G_BAR; G_SCHED;
;       G_LDB(B1, 0, 1); G_STAGE(G_SB(0, 0), b2, vb0);
;       G_BAR; G_WAIT_L(0); G_MMA(0, 1, At, B1); G_BAR;
;       G_LDA(At, 0, 1); G_STAGE(G_SA(0, 0), a2, voffA);
;       G_BAR; G_WAIT_L(0); G_MMA(1, 0, At, B0); G_BAR; G_SCHED;
;       G_STAGE(G_SB(0, 1), b2, vb1);
;       G_WAIT_V(6); G_BAR; G_MMA(1, 1, At, B1); G_BAR;
.LBB0_209:
	s_add_u32 s8, s28, s2
	v_add_u32_e32 v228, 0x10000, v212
	s_addc_u32 s9, s29, s3
	s_add_u32 s100, s8, 0x80080
	s_addc_u32 s101, s9, 0
	ds_read_b128 v[148:151], v228
	ds_read_b128 v[152:155], v228 offset:1024
	ds_read_b128 v[156:159], v228 offset:2048
	ds_read_b128 v[160:163], v228 offset:3072
	s_add_u32 s52, s8, 0x100
	s_addc_u32 s53, s9, 0
	s_and_b64 s[8:9], s[6:7], exec
	s_cselect_b32 s9, s10, s53
	s_cselect_b32 s8, s11, s52
	s_add_u32 s52, s74, s2
	s_addc_u32 s53, s75, s3
	s_and_b64 s[6:7], s[6:7], exec
	s_cselect_b32 s7, s37, s53
	s_cselect_b32 s6, s39, s52
	s_add_i32 m0, s23, 0xc000
	ds_read_b128 v[164:167], v211
	ds_read_b128 v[168:171], v211 offset:1024
	ds_read_b128 v[172:175], v211 offset:2048
	ds_read_b128 v[176:179], v211 offset:3072
	ds_read_b128 v[180:183], v211 offset:4096
	ds_read_b128 v[184:187], v211 offset:5120
	ds_read_b128 v[188:191], v211 offset:6144
	ds_read_b128 v[192:195], v211 offset:7168
	global_load_lds_dwordx4 v138, s[100:101]
	s_add_i32 m0, s23, 0xe000
	s_nop 0
	global_load_lds_dwordx4 v140, s[100:101]
	s_waitcnt lgkmcnt(8)
	s_barrier
	s_waitcnt lgkmcnt(0)
	s_waitcnt lgkmcnt(0)
	v_mfma_f32_16x16x32_bf16 v[62:65], v[148:151], v[164:167], v[62:65]
	v_mfma_f32_16x16x32_bf16 v[58:61], v[156:159], v[164:167], v[58:61]
	v_mfma_f32_16x16x32_bf16 v[54:57], v[148:151], v[172:175], v[54:57]
	v_mfma_f32_16x16x32_bf16 v[50:53], v[156:159], v[172:175], v[50:53]
	v_mfma_f32_16x16x32_bf16 v[46:49], v[148:151], v[180:183], v[46:49]
	v_mfma_f32_16x16x32_bf16 v[42:45], v[156:159], v[180:183], v[42:45]
	v_mfma_f32_16x16x32_bf16 v[38:41], v[148:151], v[188:191], v[38:41]
	v_mfma_f32_16x16x32_bf16 v[34:37], v[156:159], v[188:191], v[34:37]
	v_mfma_f32_16x16x32_bf16 v[62:65], v[152:155], v[168:171], v[62:65]
	v_mfma_f32_16x16x32_bf16 v[58:61], v[160:163], v[168:171], v[58:61]
	v_mfma_f32_16x16x32_bf16 v[54:57], v[152:155], v[176:179], v[54:57]
	v_mfma_f32_16x16x32_bf16 v[50:53], v[160:163], v[176:179], v[50:53]
	v_mfma_f32_16x16x32_bf16 v[46:49], v[152:155], v[184:187], v[46:49]
	v_mfma_f32_16x16x32_bf16 v[42:45], v[160:163], v[184:187], v[42:45]
	v_mfma_f32_16x16x32_bf16 v[38:41], v[152:155], v[192:195], v[38:41]
	v_mfma_f32_16x16x32_bf16 v[34:37], v[160:163], v[192:195], v[34:37]
	s_barrier
	s_mov_b32 m0, s25
	ds_read_b128 v[196:199], v228 offset:16384
	ds_read_b128 v[200:203], v228 offset:17408
	ds_read_b128 v[204:207], v228 offset:18432
	ds_read_b128 v[238:241], v228 offset:19456
	global_load_lds_dwordx4 v0, s[6:7]
	s_mov_b32 m0, s58
	s_nop 0
	global_load_lds_dwordx4 v136, s[6:7]
	s_barrier
	s_waitcnt lgkmcnt(0)
	s_waitcnt lgkmcnt(0)
	v_mfma_f32_16x16x32_bf16 v[30:33], v[196:199], v[164:167], v[30:33]
	v_mfma_f32_16x16x32_bf16 v[26:29], v[204:207], v[164:167], v[26:29]
	v_mfma_f32_16x16x32_bf16 v[22:25], v[196:199], v[172:175], v[22:25]
	v_mfma_f32_16x16x32_bf16 v[18:21], v[204:207], v[172:175], v[18:21]
	v_mfma_f32_16x16x32_bf16 v[14:17], v[196:199], v[180:183], v[14:17]
	v_mfma_f32_16x16x32_bf16 v[10:13], v[204:207], v[180:183], v[10:13]
	v_mfma_f32_16x16x32_bf16 v[6:9], v[196:199], v[188:191], v[6:9]
	v_mfma_f32_16x16x32_bf16 v[2:5], v[204:207], v[188:191], v[2:5]
	v_mfma_f32_16x16x32_bf16 v[30:33], v[200:203], v[168:171], v[30:33]
	v_mfma_f32_16x16x32_bf16 v[26:29], v[238:241], v[168:171], v[26:29]
	v_mfma_f32_16x16x32_bf16 v[22:25], v[200:203], v[176:179], v[22:25]
	v_mfma_f32_16x16x32_bf16 v[18:21], v[238:241], v[176:179], v[18:21]
	v_mfma_f32_16x16x32_bf16 v[14:17], v[200:203], v[184:187], v[14:17]
	v_mfma_f32_16x16x32_bf16 v[10:13], v[238:241], v[184:187], v[10:13]
	v_mfma_f32_16x16x32_bf16 v[6:9], v[200:203], v[192:195], v[6:9]
	v_mfma_f32_16x16x32_bf16 v[2:5], v[238:241], v[192:195], v[2:5]
	s_mov_b32 m0, s23
	s_barrier
	ds_read_b128 v[164:167], v211 offset:16384
	ds_read_b128 v[168:171], v211 offset:17408
	ds_read_b128 v[172:175], v211 offset:18432
	ds_read_b128 v[176:179], v211 offset:19456
	ds_read_b128 v[180:183], v211 offset:20480
	ds_read_b128 v[184:187], v211 offset:21504
	ds_read_b128 v[188:191], v211 offset:22528
	ds_read_b128 v[192:195], v211 offset:23552
	global_load_lds_dwordx4 v132, s[8:9]
	s_mov_b32 m0, s59
	s_nop 0
	global_load_lds_dwordx4 v134, s[8:9]
	s_barrier
	s_waitcnt lgkmcnt(0)
	s_waitcnt lgkmcnt(0)
	v_mfma_f32_16x16x32_bf16 v[66:69], v[148:151], v[164:167], v[66:69]
	v_mfma_f32_16x16x32_bf16 v[70:73], v[156:159], v[164:167], v[70:73]
	v_mfma_f32_16x16x32_bf16 v[74:77], v[148:151], v[172:175], v[74:77]
	v_mfma_f32_16x16x32_bf16 v[78:81], v[156:159], v[172:175], v[78:81]
	v_mfma_f32_16x16x32_bf16 v[82:85], v[148:151], v[180:183], v[82:85]
	v_mfma_f32_16x16x32_bf16 v[86:89], v[156:159], v[180:183], v[86:89]
	v_mfma_f32_16x16x32_bf16 v[90:93], v[148:151], v[188:191], v[90:93]
	v_mfma_f32_16x16x32_bf16 v[94:97], v[156:159], v[188:191], v[94:97]
	v_mfma_f32_16x16x32_bf16 v[66:69], v[152:155], v[168:171], v[66:69]
	v_mfma_f32_16x16x32_bf16 v[70:73], v[160:163], v[168:171], v[70:73]
	v_mfma_f32_16x16x32_bf16 v[74:77], v[152:155], v[176:179], v[74:77]
	v_mfma_f32_16x16x32_bf16 v[78:81], v[160:163], v[176:179], v[78:81]
	v_mfma_f32_16x16x32_bf16 v[82:85], v[152:155], v[184:187], v[82:85]
	v_mfma_f32_16x16x32_bf16 v[86:89], v[160:163], v[184:187], v[86:89]
	v_mfma_f32_16x16x32_bf16 v[90:93], v[152:155], v[192:195], v[90:93]
	v_mfma_f32_16x16x32_bf16 v[94:97], v[160:163], v[192:195], v[94:97]
	s_barrier
	s_mov_b32 m0, s60
	s_nop 0
	global_load_lds_dwordx4 v130, s[6:7]
	s_mov_b32 m0, s61
	s_nop 0
	global_load_lds_dwordx4 v142, s[6:7]
	s_waitcnt vmcnt(6)
	s_barrier
; #define G_STAGE(bufoff, gbase, voff) do { _Pragma("unroll") for (int _i = 0; _i < 2; ++_i) \
;     __builtin_amdgcn_global_load_lds((const unsigned*)((const char*)(gbase) + (voff)[_i]), (LAS unsigned*)(lds + (bufoff) + ldsw + _i * 8192), 16, 0, 0); } while (0)
; #define G_LDA(dst, b, h) do { _Pragma("unroll") for (int m = 0; m < 4; ++m) _Pragma("unroll") for (int k = 0; k < 2; ++k) dst[m][k] = *(const LAS bf16x8*)(lds + G_SA(b, h) + aoff + m * 2048 + k * 1024); } while (0)
; #define G_LDB(dst, b, h) do { _Pragma("unroll") for (int n = 0; n < 2; ++n) _Pragma("unroll") for (int k = 0; k < 2; ++k) dst[n][k] = *(const LAS bf16x8*)(lds + G_SB(b, h) + boff + n * 2048 + k * 1024); } while (0)
; #define G_MMA(ai, bj, At, Bt) do { __builtin_amdgcn_s_setprio(1); _Pragma("unroll") for (int m = 0; m < 4; ++m) _Pragma("unroll") for (int n = 0; n < 2; ++n) _Pragma("unroll") for (int k = 0; k < 2; ++k) \
;     acc[ai][bj][m][n] = __builtin_amdgcn_mfma_f32_16x16x32_bf16(Bt[n][k], At[m][k], acc[ai][bj][m][n], 0, 0, 0); __builtin_amdgcn_s_setprio(0); } while (0)
; #define G_WAIT_V(n) asm volatile("s_waitcnt vmcnt(" #n ")" ::: "memory")
; #define G_WAIT_L(n) asm volatile("s_waitcnt lgkmcnt(" #n ")" ::: "memory")
; #define G_BAR __builtin_amdgcn_s_barrier()
; #define G_SCHED __builtin_amdgcn_sched_barrier(0)
; template <int GP> DI void gemm_phase(const Params& p, int l, int which, char* smem, int wv) {
;     ...
;       G_WAIT_V(6); G_BAR; G_MMA(1, 1, At, B1); G_BAR;
;       G_LDB(B0, 1, 0); G_SCHED; G_LDA(At, 1, 0); G_STAGE(G_SA(0, 1), a2 + hstep, voffA);
;       G_WAIT_L(8); G_BAR; G_WAIT_L(0); G_MMA(0, 0, At, B0); G_BAR; G_SCHED;
;       G_LDB(B1, 1, 1); G_STAGE(G_SB(1, 0), b3, vb0);
	v_mfma_f32_16x16x32_bf16 v[98:101], v[196:199], v[164:167], v[98:101]
	v_mfma_f32_16x16x32_bf16 v[102:105], v[204:207], v[164:167], v[102:105]
	v_mfma_f32_16x16x32_bf16 v[106:109], v[196:199], v[172:175], v[106:109]
	v_mfma_f32_16x16x32_bf16 v[110:113], v[204:207], v[172:175], v[110:113]
	v_mfma_f32_16x16x32_bf16 v[114:117], v[196:199], v[180:183], v[114:117]
	v_mfma_f32_16x16x32_bf16 v[118:121], v[204:207], v[180:183], v[118:121]
	v_mfma_f32_16x16x32_bf16 v[122:125], v[196:199], v[188:191], v[122:125]
	v_mfma_f32_16x16x32_bf16 v[126:129], v[204:207], v[188:191], v[126:129]
	v_mfma_f32_16x16x32_bf16 v[98:101], v[200:203], v[168:171], v[98:101]
	v_mfma_f32_16x16x32_bf16 v[102:105], v[238:241], v[168:171], v[102:105]
	v_mfma_f32_16x16x32_bf16 v[106:109], v[200:203], v[176:179], v[106:109]
	v_mfma_f32_16x16x32_bf16 v[110:113], v[238:241], v[176:179], v[110:113]
	v_mfma_f32_16x16x32_bf16 v[114:117], v[200:203], v[184:187], v[114:117]
	v_mfma_f32_16x16x32_bf16 v[118:121], v[238:241], v[184:187], v[118:121]
	v_mfma_f32_16x16x32_bf16 v[122:125], v[200:203], v[192:195], v[122:125]
	v_mfma_f32_16x16x32_bf16 v[126:129], v[238:241], v[192:195], v[126:129]
	s_barrier
	ds_read_b128 v[148:151], v228 offset:32768
	ds_read_b128 v[152:155], v228 offset:33792
	ds_read_b128 v[156:159], v228 offset:34816
	ds_read_b128 v[160:163], v228 offset:35840
	s_add_u32 s100, s8, 0x80000
	s_addc_u32 s101, s9, 0
	s_mov_b32 m0, s62
	ds_read_b128 v[164:167], v211 offset:32768
	ds_read_b128 v[168:171], v211 offset:33792
	ds_read_b128 v[172:175], v211 offset:34816
	ds_read_b128 v[176:179], v211 offset:35840
	ds_read_b128 v[180:183], v211 offset:36864
	ds_read_b128 v[184:187], v211 offset:37888
	ds_read_b128 v[188:191], v211 offset:38912
	ds_read_b128 v[192:195], v211 offset:39936
	global_load_lds_dwordx4 v132, s[100:101]
	s_mov_b32 m0, s63
	s_nop 0
	global_load_lds_dwordx4 v134, s[100:101]
	s_waitcnt lgkmcnt(8)
	s_barrier
	s_waitcnt lgkmcnt(0)
	s_waitcnt lgkmcnt(0)
	v_mfma_f32_16x16x32_bf16 v[62:65], v[148:151], v[164:167], v[62:65]
	v_mfma_f32_16x16x32_bf16 v[58:61], v[156:159], v[164:167], v[58:61]
	v_mfma_f32_16x16x32_bf16 v[54:57], v[148:151], v[172:175], v[54:57]
	v_mfma_f32_16x16x32_bf16 v[50:53], v[156:159], v[172:175], v[50:53]
	v_mfma_f32_16x16x32_bf16 v[46:49], v[148:151], v[180:183], v[46:49]
	v_mfma_f32_16x16x32_bf16 v[42:45], v[156:159], v[180:183], v[42:45]
	v_mfma_f32_16x16x32_bf16 v[38:41], v[148:151], v[188:191], v[38:41]
	v_mfma_f32_16x16x32_bf16 v[34:37], v[156:159], v[188:191], v[34:37]
	v_mfma_f32_16x16x32_bf16 v[62:65], v[152:155], v[168:171], v[62:65]
	v_mfma_f32_16x16x32_bf16 v[58:61], v[160:163], v[168:171], v[58:61]
	v_mfma_f32_16x16x32_bf16 v[54:57], v[152:155], v[176:179], v[54:57]
	v_mfma_f32_16x16x32_bf16 v[50:53], v[160:163], v[176:179], v[50:53]
	v_mfma_f32_16x16x32_bf16 v[46:49], v[152:155], v[184:187], v[46:49]
	v_mfma_f32_16x16x32_bf16 v[42:45], v[160:163], v[184:187], v[42:45]
	v_mfma_f32_16x16x32_bf16 v[38:41], v[152:155], v[192:195], v[38:41]
	v_mfma_f32_16x16x32_bf16 v[34:37], v[160:163], v[192:195], v[34:37]
	s_barrier
	s_mov_b32 m0, s21
	s_add_u32 s100, s6, s16
	s_addc_u32 s101, s7, s17
	ds_read_b128 v[196:199], v228 offset:49152
	ds_read_b128 v[200:203], v228 offset:50176
	ds_read_b128 v[204:207], v228 offset:51200
	ds_read_b128 v[238:241], v228 offset:52224
	global_load_lds_dwordx4 v0, s[100:101]
	s_mov_b32 m0, s64
	s_nop 0
	global_load_lds_dwordx4 v136, s[100:101]
	s_barrier
; #define G_STAGE(bufoff, gbase, voff) do { _Pragma("unroll") for (int _i = 0; _i < 2; ++_i) \
;     __builtin_amdgcn_global_load_lds((const unsigned*)((const char*)(gbase) + (voff)[_i]), (LAS unsigned*)(lds + (bufoff) + ldsw + _i * 8192), 16, 0, 0); } while (0)
; #define G_LDA(dst, b, h) do { _Pragma("unroll") for (int m = 0; m < 4; ++m) _Pragma("unroll") for (int k = 0; k < 2; ++k) dst[m][k] = *(const LAS bf16x8*)(lds + G_SA(b, h) + aoff + m * 2048 + k * 1024); } while (0)
; #define G_MMA(ai, bj, At, Bt) do { __builtin_amdgcn_s_setprio(1); _Pragma("unroll") for (int m = 0; m < 4; ++m) _Pragma("unroll") for (int n = 0; n < 2; ++n) _Pragma("unroll") for (int k = 0; k < 2; ++k) \
;     acc[ai][bj][m][n] = __builtin_amdgcn_mfma_f32_16x16x32_bf16(Bt[n][k], At[m][k], acc[ai][bj][m][n], 0, 0, 0); __builtin_amdgcn_s_setprio(0); } while (0)
; #define G_WAIT_V(n) asm volatile("s_waitcnt vmcnt(" #n ")" ::: "memory")
; #define G_WAIT_L(n) asm volatile("s_waitcnt lgkmcnt(" #n ")" ::: "memory")
; #define G_BAR __builtin_amdgcn_s_barrier()
; #define G_SCHED __builtin_amdgcn_sched_barrier(0)
; template <int GP> DI void gemm_phase(const Params& p, int l, int which, char* smem, int wv) {
;     ...
;       G_BAR; G_WAIT_L(0); G_MMA(0, 1, At, B1); G_BAR;
;       G_LDA(At, 1, 1); G_STAGE(G_SA(1, 0), a3, voffA);
;       G_BAR; G_WAIT_L(0); G_MMA(1, 0, At, B0); G_BAR; G_SCHED;
;       G_STAGE(G_SB(1, 1), b3, vb1);
;       G_WAIT_V(6); G_BAR; G_MMA(1, 1, At, B1); G_BAR;
;     }
	s_waitcnt lgkmcnt(0)
	s_waitcnt lgkmcnt(0)
	v_mfma_f32_16x16x32_bf16 v[30:33], v[196:199], v[164:167], v[30:33]
	v_mfma_f32_16x16x32_bf16 v[26:29], v[204:207], v[164:167], v[26:29]
	v_mfma_f32_16x16x32_bf16 v[22:25], v[196:199], v[172:175], v[22:25]
	v_mfma_f32_16x16x32_bf16 v[18:21], v[204:207], v[172:175], v[18:21]
	v_mfma_f32_16x16x32_bf16 v[14:17], v[196:199], v[180:183], v[14:17]
	v_mfma_f32_16x16x32_bf16 v[10:13], v[204:207], v[180:183], v[10:13]
	v_mfma_f32_16x16x32_bf16 v[6:9], v[196:199], v[188:191], v[6:9]
	v_mfma_f32_16x16x32_bf16 v[2:5], v[204:207], v[188:191], v[2:5]
	v_mfma_f32_16x16x32_bf16 v[30:33], v[200:203], v[168:171], v[30:33]
	v_mfma_f32_16x16x32_bf16 v[26:29], v[238:241], v[168:171], v[26:29]
	v_mfma_f32_16x16x32_bf16 v[22:25], v[200:203], v[176:179], v[22:25]
	v_mfma_f32_16x16x32_bf16 v[18:21], v[238:241], v[176:179], v[18:21]
	v_mfma_f32_16x16x32_bf16 v[14:17], v[200:203], v[184:187], v[14:17]
	v_mfma_f32_16x16x32_bf16 v[10:13], v[238:241], v[184:187], v[10:13]
	v_mfma_f32_16x16x32_bf16 v[6:9], v[200:203], v[192:195], v[6:9]
	v_mfma_f32_16x16x32_bf16 v[2:5], v[238:241], v[192:195], v[2:5]
	s_mov_b32 m0, s65
	s_add_u32 s100, s8, s16
	s_addc_u32 s101, s9, s17
	s_barrier
	ds_read_b128 v[164:167], v211 offset:49152
	ds_read_b128 v[168:171], v211 offset:50176
	ds_read_b128 v[172:175], v211 offset:51200
	ds_read_b128 v[176:179], v211 offset:52224
	ds_read_b128 v[180:183], v211 offset:53248
	ds_read_b128 v[184:187], v211 offset:54272
	ds_read_b128 v[188:191], v211 offset:55296
	ds_read_b128 v[192:195], v211 offset:56320
	global_load_lds_dwordx4 v132, s[100:101]
	s_mov_b32 m0, s66
	s_nop 0
	global_load_lds_dwordx4 v134, s[100:101]
	s_barrier
	s_waitcnt lgkmcnt(0)
	s_waitcnt lgkmcnt(0)
	v_mfma_f32_16x16x32_bf16 v[66:69], v[148:151], v[164:167], v[66:69]
	v_mfma_f32_16x16x32_bf16 v[70:73], v[156:159], v[164:167], v[70:73]
	v_mfma_f32_16x16x32_bf16 v[74:77], v[148:151], v[172:175], v[74:77]
	v_mfma_f32_16x16x32_bf16 v[78:81], v[156:159], v[172:175], v[78:81]
	v_mfma_f32_16x16x32_bf16 v[82:85], v[148:151], v[180:183], v[82:85]
	v_mfma_f32_16x16x32_bf16 v[86:89], v[156:159], v[180:183], v[86:89]
	v_mfma_f32_16x16x32_bf16 v[90:93], v[148:151], v[188:191], v[90:93]
	v_mfma_f32_16x16x32_bf16 v[94:97], v[156:159], v[188:191], v[94:97]
	v_mfma_f32_16x16x32_bf16 v[66:69], v[152:155], v[168:171], v[66:69]
	v_mfma_f32_16x16x32_bf16 v[70:73], v[160:163], v[168:171], v[70:73]
	v_mfma_f32_16x16x32_bf16 v[74:77], v[152:155], v[176:179], v[74:77]
	v_mfma_f32_16x16x32_bf16 v[78:81], v[160:163], v[176:179], v[78:81]
	v_mfma_f32_16x16x32_bf16 v[82:85], v[152:155], v[184:187], v[82:85]
	v_mfma_f32_16x16x32_bf16 v[86:89], v[160:163], v[184:187], v[86:89]
	v_mfma_f32_16x16x32_bf16 v[90:93], v[152:155], v[192:195], v[90:93]
	v_mfma_f32_16x16x32_bf16 v[94:97], v[160:163], v[192:195], v[94:97]
	s_barrier
	s_mov_b32 m0, s67
	s_add_u32 s100, s6, s16
	s_addc_u32 s101, s7, s17
	global_load_lds_dwordx4 v130, s[100:101]
	s_mov_b32 m0, s68
	s_nop 0
	global_load_lds_dwordx4 v142, s[100:101]
	s_waitcnt vmcnt(6)
	s_barrier
	v_mfma_f32_16x16x32_bf16 v[98:101], v[196:199], v[164:167], v[98:101]
	v_mfma_f32_16x16x32_bf16 v[102:105], v[204:207], v[164:167], v[102:105]
	v_mfma_f32_16x16x32_bf16 v[106:109], v[196:199], v[172:175], v[106:109]
	v_mfma_f32_16x16x32_bf16 v[110:113], v[204:207], v[172:175], v[110:113]
	v_mfma_f32_16x16x32_bf16 v[114:117], v[196:199], v[180:183], v[114:117]
	v_mfma_f32_16x16x32_bf16 v[118:121], v[204:207], v[180:183], v[118:121]
	v_mfma_f32_16x16x32_bf16 v[122:125], v[196:199], v[188:191], v[122:125]
	v_mfma_f32_16x16x32_bf16 v[126:129], v[204:207], v[188:191], v[126:129]
	v_mfma_f32_16x16x32_bf16 v[98:101], v[200:203], v[168:171], v[98:101]
	v_mfma_f32_16x16x32_bf16 v[102:105], v[238:241], v[168:171], v[102:105]
	v_mfma_f32_16x16x32_bf16 v[106:109], v[200:203], v[176:179], v[106:109]
	v_mfma_f32_16x16x32_bf16 v[110:113], v[238:241], v[176:179], v[110:113]
	v_mfma_f32_16x16x32_bf16 v[114:117], v[200:203], v[184:187], v[114:117]
	v_mfma_f32_16x16x32_bf16 v[118:121], v[238:241], v[184:187], v[118:121]
	v_mfma_f32_16x16x32_bf16 v[122:125], v[200:203], v[192:195], v[122:125]
	v_mfma_f32_16x16x32_bf16 v[126:129], v[238:241], v[192:195], v[126:129]
	s_add_i32 s50, s50, 2
	s_add_u32 s2, s2, 0x100
	s_addc_u32 s3, s3, 0
	s_cmp_gt_u32 s50, 29
	s_barrier
	s_cbranch_scc1 .LBB0_219
